# v39 + layer-0 tail-slot item ranges evened out per converting wave (gate/up tail 7168, w_in tail 7808, gate/up-2 tail 6528)
# baseline (speedup 1.0000x reference)
; #define LAS __attribute__((address_space(3)))
; #define GW_DECL const int wv_ = launder_s(g_wave), lane = opaque_lane(), tid = (wv_ << 6) | lane, gw = BXL() * NWAVES + wv_; (void)tid; (void)lane; (void)gw
; #define BXL() ({ int _b = bx; asm volatile("" : "+s"(_b)); _b; })
; __device__ __forceinline__ void convert_range(unsigned char* lds, int lo, int hi, int w, int nworkers, int wave, int lane) {
;     const XItem* tab = (const XItem*)(lds + 8 * 16640);
;     LAS float* scr = (LAS float*)((LAS unsigned char*)lds + wave * 16640);
;     int it = lo + w; if (it >= hi) return;
;     f32x4 v[16]; float gv[16]; ItemPos p = item_load(tab, it, lane, v, gv);
; __global__ void __launch_bounds__(NTHREADS, 2) mega_fwd(KArgs a_unused) {
;     ...
;           if (((32 * 44) % G != 0) && ((32 * 18) % G != 0)) { const int rem_ = (32 * 44) % G; const int bxt_ = BXL(); if (rem_ != 0 && bxt_ >= rem_) { GW_DECL; convert_range(lds, (l == 0 ? 5632 : ITEMS_L + 5632), (l == 0 ? 10752 : ITEMS_L + 10752), (bxt_ - rem_) * NWAVES + wv_, (G - rem_) * NWAVES, wv_, lane); __syncthreads(); } }
.LBB0_479:
	v_readlane_b32 s2, v255, 5
	v_readlane_b32 s3, v255, 6
	s_andn2_b64 vcc, exec, s[2:3]
	s_mov_b32 s4, s68
	v_cndmask_b32_e64 v0, 0, 1, s[2:3]
	v_readlane_b32 s2, v255, 11
	v_readlane_b32 s3, v255, 12
	v_cmp_ne_u32_e64 s[6:7], 1, v0
	s_nop 0
	v_cndmask_b32_e64 v0, 0, 1, s[2:3]
	v_cmp_ne_u32_e64 s[2:3], 1, v0
	s_nop 1
	v_writelane_b32 v255, s2, 39
	s_nop 1
	v_writelane_b32 v255, s3, 40
	s_cbranch_vccnz .LBB0_552
	v_readlane_b32 s2, v255, 39
	v_readlane_b32 s3, v255, 40
	s_and_b64 vcc, exec, s[2:3]
	s_cbranch_vccnz .LBB0_552
	v_readlane_b32 s2, v255, 7
	v_readlane_b32 s1, v255, 4
	s_cmp_lt_i32 s2, s1
	v_readlane_b32 s3, v255, 8
	s_cbranch_scc1 .LBB0_552
	v_readlane_b32 s4, v255, 7
	v_readlane_b32 s5, v255, 8
	s_mov_b32 s3, s4
	v_readlane_b32 s4, v255, 29
	v_readlane_b32 s5, v255, 30
	s_and_b64 s[4:5], s[4:5], exec
	s_movk_i32 s5, 0x3200
	s_movk_i32 s4, 0x1600
	s_cselect_b32 s14, s5, 0x7d80
	v_readlane_b32 s5, v255, 4
	s_cselect_b32 s4, s4, 0x6980
	s_sub_i32 s2, s2, s5
	s_lshl_b32 s2, s2, 3
	s_mov_b32 s1, s64
	s_add_i32 s2, s2, s4
	s_add_i32 s15, s2, s1
	s_cmp_ge_i32 s15, s14
	v_mov_b32 v0, 0
	s_cbranch_scc1 .LBB0_551
	s_mov_b32 s2, s15
	s_mov_b32 s3, 2
	s_mov_b32 s4, 1
	s_mov_b32 s5, 0
	v_bfrev_b32_e32 v2, 1
	v_bfrev_b32_e32 v3, 1

; #define LAS __attribute__((address_space(3)))
; #define GW_DECL const int wv_ = launder_s(g_wave), lane = opaque_lane(), tid = (wv_ << 6) | lane, gw = BXL() * NWAVES + wv_; (void)tid; (void)lane; (void)gw
; #define BXL() ({ int _b = bx; asm volatile("" : "+s"(_b)); _b; })
; __device__ __forceinline__ void convert_range(unsigned char* lds, int lo, int hi, int w, int nworkers, int wave, int lane) {
;     const XItem* tab = (const XItem*)(lds + 8 * 16640);
;     LAS float* scr = (LAS float*)((LAS unsigned char*)lds + wave * 16640);
;     int it = lo + w; if (it >= hi) return;
;     f32x4 v[16]; float gv[16]; ItemPos p = item_load(tab, it, lane, v, gv);
; __global__ void __launch_bounds__(NTHREADS, 2) mega_fwd(KArgs a_unused) {
;     ...
;           if (((32 * 44) % G != 0) && ((32 * 18) % G != 0)) { const int rem_ = (32 * 18) % G; const int bxt_ = BXL(); if (rem_ != 0 && bxt_ >= rem_) { GW_DECL; convert_range(lds, (l == 0 ? 17408 : ITEMS_L + 10752), (l == 0 ? 21248 : ITEMS_L + 17408), (bxt_ - rem_) * NWAVES + wv_, (G - rem_) * NWAVES, wv_, lane); convert_range(lds, (l == 0 ? ITEMS_L : 0), (l == 0 ? ITEMS_L + 2816 : 0), (bxt_ - rem_) * NWAVES + wv_, (G - rem_) * NWAVES, wv_, lane); __syncthreads(); } } }
.LBB0_742:
	s_and_b64 vcc, exec, s[6:7]
	s_cbranch_vccnz .LBB0_884
	v_readlane_b32 s2, v255, 39
	v_readlane_b32 s3, v255, 40
	s_and_b64 vcc, exec, s[2:3]
	s_cbranch_vccnz .LBB0_884
	v_readlane_b32 s2, v255, 7
	s_mov_b32 s1, s2
	v_readlane_b32 s2, v255, 13
	s_cmp_lt_i32 s1, s2
	v_readlane_b32 s3, v255, 8
	s_cbranch_scc1 .LBB0_884
	v_readlane_b32 s2, v255, 7
	v_readlane_b32 s3, v255, 8
	s_mov_b32 s5, s2
	v_readlane_b32 s2, v255, 29
	v_readlane_b32 s3, v255, 30
	s_and_b64 s[2:3], s[2:3], exec
	s_movk_i32 s3, 0x5000
	s_movk_i32 s2, 0x3200
	s_cselect_b32 s16, s3, 0x9780
	v_readlane_b32 s3, v255, 13
	s_mov_b32 s4, s64
	s_cselect_b32 s2, s2, 0x7d80
	s_sub_i32 s1, s1, s3
	s_lshl_b32 s1, s1, 3
	v_mov_b32 v0, 0
	s_add_i32 s15, s4, s1
	s_mulk_i32 s4, 0x4100
	v_mbcnt_lo_u32_b32 v0, -1, v0
	s_add_i32 s14, s4, 0
	s_add_i32 s20, s15, s2
	v_mbcnt_hi_u32_b32 v96, -1, v0
	s_cmp_ge_i32 s20, s16
	s_cbranch_scc1 .LBB0_814
	s_mov_b32 s1, s20
	s_mov_b32 s2, 2
	s_mov_b32 s3, 1
	s_mov_b32 s4, 0
	v_bfrev_b32_e32 v0, 1
	v_bfrev_b32_e32 v2, 1

; #define LAS __attribute__((address_space(3)))
; #define GW_DECL const int wv_ = launder_s(g_wave), lane = opaque_lane(), tid = (wv_ << 6) | lane, gw = BXL() * NWAVES + wv_; (void)tid; (void)lane; (void)gw
; #define BXL() ({ int _b = bx; asm volatile("" : "+s"(_b)); _b; })
; __device__ __forceinline__ void convert_range(unsigned char* lds, int lo, int hi, int w, int nworkers, int wave, int lane) {
;     const XItem* tab = (const XItem*)(lds + 8 * 16640);
;     LAS float* scr = (LAS float*)((LAS unsigned char*)lds + wave * 16640);
;     int it = lo + w; if (it >= hi) return;
;     f32x4 v[16]; float gv[16]; ItemPos p = item_load(tab, it, lane, v, gv);
; __global__ void __launch_bounds__(NTHREADS, 2) mega_fwd(KArgs a_unused) {
;     ...
;           if (((32 * 44) % G != 0) && ((32 * 18) % G != 0)) { const int rem_ = (32 * 44) % G; const int bxt_ = BXL(); if (rem_ != 0 && bxt_ >= rem_) { GW_DECL; convert_range(lds, (l == 0 ? ITEMS_L + 2816 : ITEMS_L + 17408), (l == 0 ? ITEMS_L + 5632 : ITEMS_L + 21248), (bxt_ - rem_) * NWAVES + wv_, (G - rem_) * NWAVES, wv_, lane); __syncthreads(); } } }
.LBB0_1366:
	v_readlane_b32 s2, v255, 5
	v_readlane_b32 s3, v255, 6
	s_and_b64 vcc, exec, s[2:3]
	s_cbranch_vccz .LBB0_1439
	v_readlane_b32 s2, v255, 39
	v_readlane_b32 s3, v255, 40
	s_and_b64 vcc, exec, s[2:3]
	s_cbranch_vccnz .LBB0_1439
	v_readlane_b32 s2, v255, 7
	v_readlane_b32 s1, v255, 4
	s_cmp_lt_i32 s2, s1
	v_readlane_b32 s3, v255, 8
	s_cbranch_scc1 .LBB0_1439
	v_readlane_b32 s4, v255, 7
	v_readlane_b32 s5, v255, 8
	s_mov_b32 s3, s4
	v_readlane_b32 s4, v255, 29
	v_readlane_b32 s5, v255, 30
	s_and_b64 s[4:5], s[4:5], exec
	s_mov_b32 s5, 0xa680
	s_movk_i32 s4, 0x5000
	s_cselect_b32 s14, 0x6980, s5
	v_readlane_b32 s5, v255, 4
	s_cselect_b32 s4, s4, 0x9780
	s_sub_i32 s2, s2, s5
	s_lshl_b32 s2, s2, 3
	s_mov_b32 s1, s64
	s_add_i32 s2, s2, s4
	s_add_i32 s15, s2, s1
	s_cmp_ge_i32 s15, s14
	v_mov_b32 v0, 0
	s_cbranch_scc1 .LBB0_1438
	s_mov_b32 s2, s15
	s_mov_b32 s3, 2
	s_mov_b32 s4, 1
	s_mov_b32 s5, 0
	v_bfrev_b32_e32 v2, 1
	v_bfrev_b32_e32 v3, 1
